# attention tile loop: P packing by integer RNE bit trick (48 VALU per tile) replaced by 8 v_cvt_pk_bf16_f32 + 8 moves; same RNE rounding
# speedup vs baseline: 1.1207x; 1.0043x over previous
; #define LAS __attribute__((address_space(3)))
; DEVQ unsigned pk2(float lo, float hi) { return f2bf(lo) | (f2bf(hi) << 16); }
; DEVQ s16x4 vtr(const LAS bf16* p) { return __builtin_bit_cast(s16x4, __builtin_amdgcn_ds_read_tr16_b64_v4i16((LAS v4i16_t*)p)); }
; DEVQ void attn_unit(const bf16* qkv, bf16* O, const float* sinkp, LAS unsigned char* lds, int mb, int L, int t0, int kvh) {
;     ...
;             tmax = fmaxf(tmax, __shfl_xor(tmax, 32));
;             const float mnew = fmaxf(mrun, tmax), alpha = __builtin_amdgcn_exp2f(mrun - mnew); mrun = mnew;
;             float ps = 0.f;
; #pragma unroll
;             for (int i = 0; i < 16; ++i) { p[i] = __builtin_amdgcn_exp2f(p[i] - mnew); ps += p[i]; }
;             lrun = lrun * alpha + ps;
; #pragma unroll
;             for (int i = 0; i < 16; ++i) { o0[i] *= alpha; o1[i] *= alpha; }
;             v4u pw0, pw1;
;             pw0.x = pk2(p[0], p[1]); pw0.y = pk2(p[2], p[3]); pw0.z = pk2(p[4], p[5]); pw0.w = pk2(p[6], p[7]);
;             pw1.x = pk2(p[8], p[9]); pw1.y = pk2(p[10], p[11]); pw1.z = pk2(p[12], p[13]); pw1.w = pk2(p[14], p[15]);
;             const bf16x8 pb0 = __builtin_bit_cast(bf16x8, pw0), pb1 = __builtin_bit_cast(bf16x8, pw1);
; #pragma unroll
;             for (int blk = 0; blk < 2; ++blk) {
;                 const LAS bf16* vp = Vs + (tile * 32 + 4 * hh + ((lane & 15) >> 2)) * ATT_KSTR + blk * 32 + ((lane >> 4) & 1) * 16 + (lane & 3) * 4;
;                 const s16x4 a0 = vtr(vp), a1 = vtr(vp + 8 * ATT_KSTR), b0 = vtr(vp + 16 * ATT_KSTR), b1 = vtr(vp + 24 * ATT_KSTR);
;                 const bf16x8 vf0 = (bf16x8){a0[0], a0[1], a0[2], a0[3], a1[0], a1[1], a1[2], a1[3]}, vf1 = (bf16x8){b0[0], b0[1], b0[2], b0[3], b1[0], b1[1], b1[2], b1[3]};
;                 if (blk == 0) { o0 = __builtin_amdgcn_mfma_f32_32x32x16_bf16(vf0, pb0, o0, 0, 0, 0); o0 = __builtin_amdgcn_mfma_f32_32x32x16_bf16(vf1, pb1, o0, 0, 0, 0); }
;                 else          { o1 = __builtin_amdgcn_mfma_f32_32x32x16_bf16(vf0, pb0, o1, 0, 0, 0); o1 = __builtin_amdgcn_mfma_f32_32x32x16_bf16(vf1, pb1, o1, 0, 0, 0); }
.LBB0_125:
	s_or_b64 exec, exec, s[14:15]
	s_nop 5
	ds_bpermute_b32 v32, v97, v64
	s_waitcnt lgkmcnt(0)
	v_max3_f32 v33, v107, v64, v32
	v_sub_f32_e32 v34, v76, v33
	v_exp_f32_e32 v34, v34
	v_sub_f32_e32 v35, v77, v33
	v_exp_f32_e32 v35, v35
	v_sub_f32_e32 v36, v78, v33
	v_exp_f32_e32 v36, v36
	v_sub_f32_e32 v37, v79, v33
	v_exp_f32_e32 v37, v37
	v_sub_f32_e32 v38, v80, v33
	v_exp_f32_e32 v38, v38
	v_sub_f32_e32 v39, v81, v33
	v_add_f32_e32 v77, 0, v34
	v_exp_f32_e32 v39, v39
	v_sub_f32_e32 v40, v82, v33
	v_add_f32_e32 v77, v35, v77
	v_exp_f32_e32 v40, v40
	v_sub_f32_e32 v41, v83, v33
	v_add_f32_e32 v77, v36, v77
	v_exp_f32_e32 v41, v41
	v_sub_f32_e32 v42, v84, v33
	v_add_f32_e32 v77, v37, v77
	v_exp_f32_e32 v42, v42
	v_sub_f32_e32 v43, v85, v33
	v_add_f32_e32 v77, v38, v77
	v_exp_f32_e32 v43, v43
	v_sub_f32_e32 v44, v86, v33
	v_add_f32_e32 v77, v39, v77
	v_exp_f32_e32 v44, v44
	v_sub_f32_e32 v45, v87, v33
	v_add_f32_e32 v77, v40, v77
	v_exp_f32_e32 v45, v45
	v_sub_f32_e32 v46, v88, v33
	v_add_f32_e32 v77, v41, v77
	v_exp_f32_e32 v46, v46
	v_sub_f32_e32 v47, v89, v33
	v_add_f32_e32 v77, v42, v77
	v_exp_f32_e32 v47, v47
	v_sub_f32_e32 v64, v90, v33
	v_add_f32_e32 v77, v43, v77
	v_exp_f32_e32 v64, v64
	v_sub_f32_e32 v76, v91, v33
	v_add_f32_e32 v77, v44, v77
	v_exp_f32_e32 v76, v76
	v_add_f32_e32 v77, v45, v77
	v_add_f32_e32 v77, v46, v77
	v_add_f32_e32 v77, v47, v77
	v_add_f32_e32 v77, v64, v77
	v_add_f32_e32 v80, v76, v77
	v_cvt_pk_bf16_f32 v138, v38, v39
	v_cvt_pk_bf16_f32 v139, v36, v37
	v_cvt_pk_bf16_f32 v140, v40, v41
	v_cvt_pk_bf16_f32 v141, v46, v47
	v_cvt_pk_bf16_f32 v142, v44, v45
	v_cvt_pk_bf16_f32 v143, v64, v76
	v_cvt_pk_bf16_f32 v144, v42, v43
	v_cvt_pk_bf16_f32 v145, v34, v35
	v_mov_b32_e32 v36, v138
	v_mov_b32_e32 v35, v139
	v_mov_b32_e32 v37, v140
	v_add_u32_e32 v46, 0, v111
	v_mov_b32_e32 v40, v141
	v_mov_b32_e32 v39, v142
	v_add_u32_e32 v44, 0x10080, v46
	v_add_u32_e32 v47, 0x10500, v46
	v_mov_b32_e32 v41, v143
	v_mov_b32_e32 v38, v144
	ds_read_b64_tr_b16 v[42:43], v46 offset:64512
	ds_read_b64_tr_b16 v[76:77], v47
	ds_read_b64_tr_b16 v[44:45], v44
	v_sub_f32_e32 v32, v107, v33
	v_exp_f32_e32 v32, v32
	v_mov_b32_e32 v34, v145
	v_add_u32_e32 v47, 0x10980, v46
	v_pk_mul_f32 v[30:31], v[30:31], v[32:33] op_sel_hi:[1,0]
	v_pk_mul_f32 v[28:29], v[28:29], v[32:33] op_sel_hi:[1,0]
	v_pk_mul_f32 v[26:27], v[26:27], v[32:33] op_sel_hi:[1,0]
	v_pk_mul_f32 v[24:25], v[24:25], v[32:33] op_sel_hi:[1,0]
	v_pk_mul_f32 v[22:23], v[22:23], v[32:33] op_sel_hi:[1,0]
	v_pk_mul_f32 v[20:21], v[20:21], v[32:33] op_sel_hi:[1,0]
	v_pk_mul_f32 v[18:19], v[18:19], v[32:33] op_sel_hi:[1,0]
	v_pk_mul_f32 v[16:17], v[16:17], v[32:33] op_sel_hi:[1,0]
	ds_read_b64_tr_b16 v[78:79], v47
	v_pk_mul_f32 v[14:15], v[14:15], v[32:33] op_sel_hi:[1,0]
	s_waitcnt lgkmcnt(1)
	v_mfma_f32_32x32x16_bf16 v[16:31], v[42:45], v[34:37], v[16:31]
	v_add_u32_e32 v44, 0x100c0, v46
	ds_read_b64_tr_b16 v[42:43], v46 offset:64576
	ds_read_b64_tr_b16 v[44:45], v44
	v_add_u32_e32 v47, 0x10540, v46
	v_add_u32_e32 v46, 0x109c0, v46
	v_pk_mul_f32 v[12:13], v[12:13], v[32:33] op_sel_hi:[1,0]
	v_pk_mul_f32 v[10:11], v[10:11], v[32:33] op_sel_hi:[1,0]
	v_pk_mul_f32 v[8:9], v[8:9], v[32:33] op_sel_hi:[1,0]
	v_pk_mul_f32 v[6:7], v[6:7], v[32:33] op_sel_hi:[1,0]
	v_pk_mul_f32 v[4:5], v[4:5], v[32:33] op_sel_hi:[1,0]
	v_pk_mul_f32 v[2:3], v[2:3], v[32:33] op_sel_hi:[1,0]
	v_pk_mul_f32 v[0:1], v[0:1], v[32:33] op_sel_hi:[1,0]
	s_waitcnt lgkmcnt(2)
	v_mfma_f32_32x32x16_bf16 v[16:31], v[76:79], v[38:41], v[16:31]
	ds_read_b64_tr_b16 v[76:77], v47
	ds_read_b64_tr_b16 v[78:79], v46
	v_fmac_f32_e32 v80, v106, v32
	v_mov_b32_e32 v107, v33
	v_mov_b32_e32 v106, v80
	s_waitcnt lgkmcnt(2)
	v_mfma_f32_32x32x16_bf16 v[0:15], v[42:45], v[34:37], v[0:15]
	s_waitcnt lgkmcnt(0)
	v_mfma_f32_32x32x16_bf16 v[0:15], v[76:79], v[38:41], v[0:15]
